# EpiResid unit transition: exact counted wait vmcnt(24) for the hoisted residual loads (16 dwordx4 + 8 short stores are younger) instead of vmcnt(16)
# speedup vs baseline: 1.0095x; 1.0046x over previous
; DI float bflo(unsigned u) { return __uint_as_float(u << 16); }
; DI float bfhi(unsigned u) { return __uint_as_float(u & 0xffff0000u); }
;   DI void init(f32x4 (&acc)[2][2][4][2], const Unit&, int, int, int, int) const { acc_zero(acc); }
;   DI void init(f32x4 (&acc)[2][2][4][2], const Unit&, int, int, int, int) const { acc_zero(acc); }
;   DI void init(f32x4 (&acc)[2][2][4][2], const Unit& u, int wr, int wc, int fr, int fq) const {
;     const int row0 = u.pm * BM + wr * 64 + fr, col0 = u.pn * BM + wc * 32 + 8 * fq; const float ic = 1.f / coef;
; #pragma unroll
;     for (int ai = 0; ai < 2; ++ai)
; #pragma unroll
;       for (int m = 0; m < 4; ++m) { const bf16_t* rowp = src + (size_t)(row0 + ai * HALF + m * 16) * DM + col0;
; #pragma unroll
;         for (int bj = 0; bj < 2; ++bj) { const u32x4 w = *(const u32x4*)(rowp + bj * HALF);
;           acc[ai][bj][m][0] = (f32x4){bflo(w.x), bfhi(w.x), bflo(w.y), bfhi(w.y)} * ic; acc[ai][bj][m][1] = (f32x4){bflo(w.z), bfhi(w.z), bflo(w.w), bfhi(w.w)} * ic; } }
.LBB0_528:
	s_or_b64 exec, exec, s[28:29]
	s_mov_b64 s[0:1], -1
	s_and_b64 vcc, vcc, exec
	s_cbranch_vccz .LBB0_503
	s_waitcnt vmcnt(24)
	s_waitcnt lgkmcnt(0)
	v_lshlrev_b32_e32 v118, 16, v166
	v_and_b32_e32 v119, 0xffff0000, v166
	v_lshlrev_b32_e32 v120, 16, v167
	v_and_b32_e32 v121, 0xffff0000, v167
	v_lshlrev_b32_e32 v122, 16, v170
	v_and_b32_e32 v123, 0xffff0000, v170
	v_lshlrev_b32_e32 v124, 16, v171
	v_and_b32_e32 v125, 0xffff0000, v171
	v_lshlrev_b32_e32 v126, 16, v172
	v_and_b32_e32 v127, 0xffff0000, v172
	v_lshlrev_b32_e32 v128, 16, v173
	v_and_b32_e32 v129, 0xffff0000, v173
	v_lshlrev_b32_e32 v110, 16, v168
	v_and_b32_e32 v111, 0xffff0000, v168
	v_lshlrev_b32_e32 v112, 16, v169
	v_and_b32_e32 v113, 0xffff0000, v169
	v_lshlrev_b32_e32 v90, 16, v174
	v_and_b32_e32 v91, 0xffff0000, v174
	v_lshlrev_b32_e32 v92, 16, v175
	v_and_b32_e32 v93, 0xffff0000, v175
	v_lshlrev_b32_e32 v82, 16, v176
	v_and_b32_e32 v83, 0xffff0000, v176
	v_lshlrev_b32_e32 v84, 16, v177
	v_and_b32_e32 v85, 0xffff0000, v177
	v_lshlrev_b32_e32 v102, 16, v178
	v_and_b32_e32 v103, 0xffff0000, v178
	v_lshlrev_b32_e32 v104, 16, v179
	v_and_b32_e32 v105, 0xffff0000, v179
	v_lshlrev_b32_e32 v114, 16, v180
	v_and_b32_e32 v115, 0xffff0000, v180
	v_lshlrev_b32_e32 v116, 16, v181
	v_and_b32_e32 v117, 0xffff0000, v181
	v_lshlrev_b32_e32 v62, 16, v182
	v_and_b32_e32 v63, 0xffff0000, v182
	v_lshlrev_b32_e32 v64, 16, v183
	v_and_b32_e32 v65, 0xffff0000, v183
	v_lshlrev_b32_e32 v50, 16, v184
	v_and_b32_e32 v51, 0xffff0000, v184
	v_lshlrev_b32_e32 v52, 16, v185
	v_and_b32_e32 v53, 0xffff0000, v185
	v_lshlrev_b32_e32 v86, 16, v186
	v_and_b32_e32 v87, 0xffff0000, v186
	v_lshlrev_b32_e32 v88, 16, v187
	v_and_b32_e32 v89, 0xffff0000, v187
	v_lshlrev_b32_e32 v98, 16, v188
	v_and_b32_e32 v99, 0xffff0000, v188
	v_lshlrev_b32_e32 v100, 16, v189
	v_and_b32_e32 v101, 0xffff0000, v189
	v_lshlrev_b32_e32 v42, 16, v190
	v_and_b32_e32 v43, 0xffff0000, v190
	v_lshlrev_b32_e32 v44, 16, v191
	v_and_b32_e32 v45, 0xffff0000, v191
	v_lshlrev_b32_e32 v22, 16, v192
	v_and_b32_e32 v23, 0xffff0000, v192
	v_lshlrev_b32_e32 v24, 16, v193
	v_and_b32_e32 v25, 0xffff0000, v193
	v_lshlrev_b32_e32 v58, 16, v198
	v_and_b32_e32 v59, 0xffff0000, v198
	v_lshlrev_b32_e32 v60, 16, v199
	v_and_b32_e32 v61, 0xffff0000, v199
	v_lshlrev_b32_e32 v74, 16, v200
	v_and_b32_e32 v75, 0xffff0000, v200
	v_lshlrev_b32_e32 v76, 16, v201
	v_and_b32_e32 v77, 0xffff0000, v201
	v_lshlrev_b32_e32 v38, 16, v194
	v_and_b32_e32 v39, 0xffff0000, v194
	v_lshlrev_b32_e32 v40, 16, v195
	v_and_b32_e32 v41, 0xffff0000, v195
	v_lshlrev_b32_e32 v18, 16, v196
	v_and_b32_e32 v19, 0xffff0000, v196
	v_lshlrev_b32_e32 v20, 16, v197
	v_and_b32_e32 v21, 0xffff0000, v197
	v_lshlrev_b32_e32 v54, 16, v202
	v_and_b32_e32 v55, 0xffff0000, v202
	v_lshlrev_b32_e32 v56, 16, v203
	v_and_b32_e32 v57, 0xffff0000, v203
	v_lshlrev_b32_e32 v66, 16, v204
	v_and_b32_e32 v67, 0xffff0000, v204
	v_lshlrev_b32_e32 v68, 16, v205
	v_and_b32_e32 v69, 0xffff0000, v205
	v_lshlrev_b32_e32 v10, 16, v206
	v_and_b32_e32 v11, 0xffff0000, v206
	v_lshlrev_b32_e32 v12, 16, v207
	v_and_b32_e32 v13, 0xffff0000, v207
	v_lshlrev_b32_e32 v2, 16, v208
	v_and_b32_e32 v3, 0xffff0000, v208
	v_lshlrev_b32_e32 v4, 16, v209
	v_and_b32_e32 v5, 0xffff0000, v209
	v_lshlrev_b32_e32 v94, 16, v210
	v_and_b32_e32 v95, 0xffff0000, v210
	v_lshlrev_b32_e32 v96, 16, v211
	v_and_b32_e32 v97, 0xffff0000, v211
	v_lshlrev_b32_e32 v106, 16, v212
	v_and_b32_e32 v107, 0xffff0000, v212
	v_lshlrev_b32_e32 v108, 16, v213
	v_and_b32_e32 v109, 0xffff0000, v213
	v_lshlrev_b32_e32 v46, 16, v214
	v_and_b32_e32 v47, 0xffff0000, v214
	v_lshlrev_b32_e32 v48, 16, v215
	v_and_b32_e32 v49, 0xffff0000, v215
	v_lshlrev_b32_e32 v30, 16, v216
	v_and_b32_e32 v31, 0xffff0000, v216
	v_lshlrev_b32_e32 v32, 16, v217
	v_and_b32_e32 v33, 0xffff0000, v217
	v_lshlrev_b32_e32 v70, 16, v218
	v_and_b32_e32 v71, 0xffff0000, v218
	v_lshlrev_b32_e32 v72, 16, v219
	v_and_b32_e32 v73, 0xffff0000, v219
	v_lshlrev_b32_e32 v78, 16, v220
	v_and_b32_e32 v79, 0xffff0000, v220
	v_lshlrev_b32_e32 v80, 16, v221
	v_and_b32_e32 v81, 0xffff0000, v221
	v_lshlrev_b32_e32 v14, 16, v238
	v_and_b32_e32 v15, 0xffff0000, v238
	v_lshlrev_b32_e32 v16, 16, v239
	v_and_b32_e32 v17, 0xffff0000, v239
	v_lshlrev_b32_e32 v6, 16, v240
	v_and_b32_e32 v7, 0xffff0000, v240
	v_lshlrev_b32_e32 v8, 16, v241
	v_and_b32_e32 v9, 0xffff0000, v241
	v_lshlrev_b32_e32 v26, 16, v242
	v_and_b32_e32 v27, 0xffff0000, v242
	v_lshlrev_b32_e32 v28, 16, v243
	v_and_b32_e32 v29, 0xffff0000, v243
	v_lshlrev_b32_e32 v34, 16, v244
	v_and_b32_e32 v35, 0xffff0000, v244
	v_lshlrev_b32_e32 v36, 16, v245
	v_and_b32_e32 v37, 0xffff0000, v245
	s_mov_b32 s0, 0x0
	s_mov_b32 s1, 0x0
	s_branch .LBB0_503

; DI float bflo(unsigned u) { return __uint_as_float(u << 16); }
; DI float bfhi(unsigned u) { return __uint_as_float(u & 0xffff0000u); }
;   DI void init(f32x4 (&acc)[2][2][4][2], const Unit&, int, int, int, int) const { acc_zero(acc); }
;   DI void init(f32x4 (&acc)[2][2][4][2], const Unit&, int, int, int, int) const { acc_zero(acc); }
;   DI void init(f32x4 (&acc)[2][2][4][2], const Unit& u, int wr, int wc, int fr, int fq) const {
;     const int row0 = u.pm * BM + wr * 64 + fr, col0 = u.pn * BM + wc * 32 + 8 * fq; const float ic = 1.f / coef;
; #pragma unroll
;     for (int ai = 0; ai < 2; ++ai)
; #pragma unroll
;       for (int m = 0; m < 4; ++m) { const bf16_t* rowp = src + (size_t)(row0 + ai * HALF + m * 16) * DM + col0;
; #pragma unroll
;         for (int bj = 0; bj < 2; ++bj) { const u32x4 w = *(const u32x4*)(rowp + bj * HALF);
;           acc[ai][bj][m][0] = (f32x4){bflo(w.x), bfhi(w.x), bflo(w.y), bfhi(w.y)} * ic; acc[ai][bj][m][1] = (f32x4){bflo(w.z), bfhi(w.z), bflo(w.w), bfhi(w.w)} * ic; } }
.LBB0_701:
	s_or_b64 exec, exec, s[30:31]
	s_mov_b64 s[28:29], -1
	s_and_b64 vcc, exec, s[38:39]
	s_cbranch_vccz .LBB0_672
	s_waitcnt vmcnt(24)
	s_waitcnt lgkmcnt(0)
	v_lshlrev_b32_e32 v126, 16, v166
	v_and_b32_e32 v127, 0xffff0000, v166
	v_lshlrev_b32_e32 v128, 16, v167
	v_and_b32_e32 v129, 0xffff0000, v167
	v_lshlrev_b32_e32 v118, 16, v170
	v_and_b32_e32 v119, 0xffff0000, v170
	v_lshlrev_b32_e32 v120, 16, v171
	v_and_b32_e32 v121, 0xffff0000, v171
	v_lshlrev_b32_e32 v122, 16, v168
	v_and_b32_e32 v123, 0xffff0000, v168
	v_lshlrev_b32_e32 v124, 16, v169
	v_and_b32_e32 v125, 0xffff0000, v169
	v_lshlrev_b32_e32 v114, 16, v172
	v_and_b32_e32 v115, 0xffff0000, v172
	v_lshlrev_b32_e32 v116, 16, v173
	v_and_b32_e32 v117, 0xffff0000, v173
	v_lshlrev_b32_e32 v110, 16, v174
	v_and_b32_e32 v111, 0xffff0000, v174
	v_lshlrev_b32_e32 v112, 16, v175
	v_and_b32_e32 v113, 0xffff0000, v175
	v_lshlrev_b32_e32 v106, 16, v176
	v_and_b32_e32 v107, 0xffff0000, v176
	v_lshlrev_b32_e32 v108, 16, v177
	v_and_b32_e32 v109, 0xffff0000, v177
	v_lshlrev_b32_e32 v102, 16, v178
	v_and_b32_e32 v103, 0xffff0000, v178
	v_lshlrev_b32_e32 v104, 16, v179
	v_and_b32_e32 v105, 0xffff0000, v179
	v_lshlrev_b32_e32 v98, 16, v180
	v_and_b32_e32 v99, 0xffff0000, v180
	v_lshlrev_b32_e32 v100, 16, v181
	v_and_b32_e32 v101, 0xffff0000, v181
	v_lshlrev_b32_e32 v94, 16, v182
	v_and_b32_e32 v95, 0xffff0000, v182
	v_lshlrev_b32_e32 v96, 16, v183
	v_and_b32_e32 v97, 0xffff0000, v183
	v_lshlrev_b32_e32 v90, 16, v184
	v_and_b32_e32 v91, 0xffff0000, v184
	v_lshlrev_b32_e32 v92, 16, v185
	v_and_b32_e32 v93, 0xffff0000, v185
	v_lshlrev_b32_e32 v86, 16, v186
	v_and_b32_e32 v87, 0xffff0000, v186
	v_lshlrev_b32_e32 v88, 16, v187
	v_and_b32_e32 v89, 0xffff0000, v187
	v_lshlrev_b32_e32 v82, 16, v188
	v_and_b32_e32 v83, 0xffff0000, v188
	v_lshlrev_b32_e32 v84, 16, v189
	v_and_b32_e32 v85, 0xffff0000, v189
	v_lshlrev_b32_e32 v78, 16, v190
	v_and_b32_e32 v79, 0xffff0000, v190
	v_lshlrev_b32_e32 v80, 16, v191
	v_and_b32_e32 v81, 0xffff0000, v191
	v_lshlrev_b32_e32 v74, 16, v192
	v_and_b32_e32 v75, 0xffff0000, v192
	v_lshlrev_b32_e32 v76, 16, v193
	v_and_b32_e32 v77, 0xffff0000, v193
	v_lshlrev_b32_e32 v54, 16, v202
	v_lshlrev_b32_e32 v62, 16, v194
	v_and_b32_e32 v63, 0xffff0000, v194
	v_lshlrev_b32_e32 v70, 16, v198
	v_and_b32_e32 v71, 0xffff0000, v198
	v_lshlrev_b32_e32 v72, 16, v199
	v_and_b32_e32 v73, 0xffff0000, v199
	v_lshlrev_b32_e32 v66, 16, v200
	v_and_b32_e32 v67, 0xffff0000, v200
	v_lshlrev_b32_e32 v68, 16, v201
	v_and_b32_e32 v69, 0xffff0000, v201
	v_lshlrev_b32_e32 v64, 16, v195
	v_and_b32_e32 v65, 0xffff0000, v195
	v_lshlrev_b32_e32 v58, 16, v196
	v_and_b32_e32 v59, 0xffff0000, v196
	v_lshlrev_b32_e32 v60, 16, v197
	v_and_b32_e32 v61, 0xffff0000, v197
	v_and_b32_e32 v55, 0xffff0000, v202
	v_lshlrev_b32_e32 v56, 16, v203
	v_and_b32_e32 v57, 0xffff0000, v203
	v_lshlrev_b32_e32 v50, 16, v204
	v_and_b32_e32 v51, 0xffff0000, v204
	v_lshlrev_b32_e32 v52, 16, v205
	v_and_b32_e32 v53, 0xffff0000, v205
	v_lshlrev_b32_e32 v46, 16, v206
	v_and_b32_e32 v47, 0xffff0000, v206
	v_lshlrev_b32_e32 v48, 16, v207
	v_and_b32_e32 v49, 0xffff0000, v207
	v_lshlrev_b32_e32 v42, 16, v208
	v_and_b32_e32 v43, 0xffff0000, v208
	v_lshlrev_b32_e32 v44, 16, v209
	v_and_b32_e32 v45, 0xffff0000, v209
	v_lshlrev_b32_e32 v38, 16, v210
	v_and_b32_e32 v39, 0xffff0000, v210
	v_lshlrev_b32_e32 v40, 16, v211
	v_and_b32_e32 v41, 0xffff0000, v211
	v_lshlrev_b32_e32 v34, 16, v212
	v_and_b32_e32 v35, 0xffff0000, v212
	v_lshlrev_b32_e32 v36, 16, v213
	v_and_b32_e32 v37, 0xffff0000, v213
	v_lshlrev_b32_e32 v30, 16, v214
	v_and_b32_e32 v31, 0xffff0000, v214
	v_lshlrev_b32_e32 v32, 16, v215
	v_and_b32_e32 v33, 0xffff0000, v215
	v_lshlrev_b32_e32 v26, 16, v216
	v_and_b32_e32 v27, 0xffff0000, v216
	v_lshlrev_b32_e32 v28, 16, v217
	v_and_b32_e32 v29, 0xffff0000, v217
	v_lshlrev_b32_e32 v22, 16, v218
	v_and_b32_e32 v23, 0xffff0000, v218
	v_lshlrev_b32_e32 v24, 16, v219
	v_and_b32_e32 v25, 0xffff0000, v219
	v_lshlrev_b32_e32 v18, 16, v220
	v_and_b32_e32 v19, 0xffff0000, v220
	v_lshlrev_b32_e32 v20, 16, v221
	v_and_b32_e32 v21, 0xffff0000, v221
	v_lshlrev_b32_e32 v14, 16, v238
	v_and_b32_e32 v15, 0xffff0000, v238
	v_lshlrev_b32_e32 v16, 16, v239
	v_and_b32_e32 v17, 0xffff0000, v239
	v_lshlrev_b32_e32 v10, 16, v240
	v_and_b32_e32 v11, 0xffff0000, v240
	v_lshlrev_b32_e32 v12, 16, v241
	v_and_b32_e32 v13, 0xffff0000, v241
	v_lshlrev_b32_e32 v6, 16, v242
	v_and_b32_e32 v7, 0xffff0000, v242
	v_lshlrev_b32_e32 v8, 16, v243
	v_and_b32_e32 v9, 0xffff0000, v243
	v_lshlrev_b32_e32 v2, 16, v244
	v_and_b32_e32 v3, 0xffff0000, v244
	v_lshlrev_b32_e32 v4, 16, v245
	v_and_b32_e32 v5, 0xffff0000, v245
	s_mov_b32 s9, 0x58000
	s_mov_b32 s22, 0x58000
	s_mov_b32 s23, 0x0
	s_mov_b32 s28, 0x0
	s_mov_b32 s29, 0x0
	s_branch .LBB0_672
